# phases 2/3: GEMM-first vs mixer-first workgroups chosen by blockIdx bit 5 (run 1)
# baseline (speedup 1.0000x reference)
;     __device__ bool next(int i, Unit& u) const { const int L = i * G + c; if (L >= 256) return false; u.pm = L; u.pn = L >> 3; return true; }
; #define GATES_ROUNDS(R0, R1) do { pg8::Gemm g{(const bf16_t*)(ws + WS_XB), (const bf16_t*)(ws + WS_WIN) + (size_t)NPROJ * 1024, 1024, 1024, 1024}; pg8::RoundRange S; S.base.init(MROWS, 2048, G, bx); S.r0 = (R0); S.r1 = (R1); \
;         Epi<EM_GATES> E{ws, nullptr, nullptr, nullptr, nullptr, 0, lds}; pg8::gemm_phase(lds, g, S, E, wave); } while (0)
;     __device__ bool next(int i, Unit& u) const {
;         const long L = (long)i * G + c; if (L >= nwg) return false;
;         int wgid = (int)L; { const int q = nwg / NXCD, r = nwg % NXCD, xcd = wgid % NXCD, off = wgid / NXCD; wgid = (xcd < r ? xcd * (q + 1) : r * (q + 1) + (xcd - r) * q) + off; }
;         const int nig = WGM * nN, gid = wgid / nig, fm = gid * WGM, gsz = (nM - fm) < WGM ? (nM - fm) : WGM;
;         u.pm = fm + ((wgid % nig) % gsz); u.pn = (wgid % nig) / gsz; return true;
;     }
;     __device__ bool next(int i, Unit& u) const { if (r0 + i >= r1) return false; return base.next(r0 + i, u); }
; __global__ void __launch_bounds__(NTHR, 2) fwd_megakernel(Prm P) {
;     ...
;     const bool local_ok = __builtin_amdgcn_readfirstlane((int)__hip_atomic_load((unsigned*)(ws + WS_CTL) + XL_BAD, __ATOMIC_RELAXED, __HIP_MEMORY_SCOPE_AGENT)) == 0 && IN(0) && IN(2);
;     ...
;     if (IN(2)) {
;         if (bx & 1) GATES_ROUNDS(0, 2);
.LBB0_653:
	v_mov_b32_e32 v0, 0x1f60a000
	global_load_dword v0, v0, s[92:93] offset:2048 sc1
	v_readlane_b32 s4, v255, 3
	v_readlane_b32 s5, v255, 4
	s_cmp_lt_i32 s4, 3
	s_cselect_b64 s[4:5], -1, 0
	s_and_b64 s[18:19], s[4:5], s[76:77]
	v_readlane_b32 s6, v255, 5
	v_readlane_b32 s7, v255, 6
	s_andn2_b64 vcc, exec, s[18:19]
	s_waitcnt vmcnt(0)
	v_readfirstlane_b32 s2, v0
	s_nop 1
	v_writelane_b32 v255, s2, 15
	s_cbranch_vccnz .LBB0_735
	s_bitcmp0_b32 s66, 5
	s_cselect_b64 s[20:21], -1, 0
	s_and_b64 vcc, exec, s[20:21]
	s_cbranch_vccnz .LBB0_680
	v_readlane_b32 s2, v255, 9
	v_mbcnt_lo_u32_b32 v0, -1, 0
	v_mbcnt_hi_u32_b32 v0, -1, v0
	s_cmpk_gt_i32 s66, 0x3ff
	s_nop 0
	v_add_u32_e32 v8, s2, v0
	s_cbranch_scc1 .LBB0_680
	s_ashr_i32 s2, s66, 31
	s_lshr_b32 s4, s2, 29
	s_add_i32 s7, s66, s4
	s_and_b32 s4, s7, -8
	s_sub_i32 s8, s66, s4
	s_cmp_gt_i32 s8, -1
	s_cbranch_scc0 .LBB0_658
	s_lshl_b32 s6, s8, 7
	s_cbranch_execz .LBB0_659
	s_branch .LBB0_660

;     __device__ bool next(int i, Unit& u) const { const int L = i * G + c; if (L >= 256) return false; u.pm = L; u.pn = L >> 3; return true; }
; #define GATES_ROUNDS(R0, R1) do { pg8::Gemm g{(const bf16_t*)(ws + WS_XB), (const bf16_t*)(ws + WS_WIN) + (size_t)NPROJ * 1024, 1024, 1024, 1024}; pg8::RoundRange S; S.base.init(MROWS, 2048, G, bx); S.r0 = (R0); S.r1 = (R1); \
;         Epi<EM_GATES> E{ws, nullptr, nullptr, nullptr, nullptr, 0, lds}; pg8::gemm_phase(lds, g, S, E, wave); } while (0)
;     __device__ bool next(int i, Unit& u) const {
;         const long L = (long)i * G + c; if (L >= nwg) return false;
;         int wgid = (int)L; { const int q = nwg / NXCD, r = nwg % NXCD, xcd = wgid % NXCD, off = wgid / NXCD; wgid = (xcd < r ? xcd * (q + 1) : r * (q + 1) + (xcd - r) * q) + off; }
;         const int nig = WGM * nN, gid = wgid / nig, fm = gid * WGM, gsz = (nM - fm) < WGM ? (nM - fm) : WGM;
;         u.pm = fm + ((wgid % nig) % gsz); u.pn = (wgid % nig) / gsz; return true;
;     }
;     __device__ bool next(int i, Unit& u) const { if (r0 + i >= r1) return false; return base.next(r0 + i, u); }
; __global__ void __launch_bounds__(NTHR, 2) fwd_megakernel(Prm P) {
;     ...
;     if (IN(3)) {
;         if (!(bx & 1)) GATES_ROUNDS(2, 4);
.LBB0_791:
	v_readlane_b32 s8, v255, 3
	s_cmp_lt_i32 s8, 4
	s_cselect_b64 s[6:7], -1, 0
	s_and_b64 s[4:5], s[6:7], s[4:5]
	v_readlane_b32 s9, v255, 4
	v_readlane_b32 s10, v255, 5
	v_readlane_b32 s11, v255, 6
	v_writelane_b32 v255, s4, 16
	s_andn2_b64 vcc, exec, s[4:5]
	s_nop 0
	v_writelane_b32 v255, s5, 17
	s_cbranch_vccnz .LBB0_870
	s_bitcmp1_b32 s66, 5
	s_cselect_b64 s[4:5], -1, 0
	v_writelane_b32 v255, s4, 18
	s_and_b64 vcc, exec, s[4:5]
	s_nop 0
	v_writelane_b32 v255, s5, 19
	s_cbranch_vccnz .LBB0_811
	v_readlane_b32 s4, v255, 1
	v_readlane_b32 s5, v255, 2
	s_ashr_i32 s5, s4, 31
	s_lshl_b64 s[6:7], s[4:5], 1
	s_ashr_i32 s5, s66, 31
	v_mbcnt_lo_u32_b32 v0, -1, 0
	v_mbcnt_hi_u32_b32 v0, -1, v0
	v_readlane_b32 s2, v255, 9
	s_add_u32 s6, s6, s66
	s_addc_u32 s7, s7, s5
	v_add_u32_e32 v14, s2, v0
	v_mov_b64_e32 v[0:1], 0x3ff
	v_cmp_gt_i64_e32 vcc, s[6:7], v[0:1]
	s_cbranch_vccnz .LBB0_811
	s_ashr_i32 s2, s6, 31
	s_lshr_b32 s2, s2, 29
	s_add_i32 s8, s6, s2
	s_and_b32 s2, s8, -8
	s_sub_i32 s2, s6, s2
	s_cmp_gt_i32 s2, -1
	s_cbranch_scc0 .LBB0_796
	s_lshl_b32 s9, s2, 7
	s_ashr_i32 s6, s8, 3
	s_cbranch_execz .LBB0_797
	s_branch .LBB0_798
